# diff-attn K/V staging via LDS-DMA (global_load_lds_dwordx4, source-side swizzle) instead of global_load+ds_write_b128; plus earlier VALU trims and NA row clamp
# speedup vs baseline: 1.0077x; 1.0077x over previous
; #define ALAS __attribute__((address_space(3)))
; template <int NC> __device__ __forceinline__ int v_st(int k, int c) { const int kk = (k & ~0xC) | ((k & 4) << 1) | ((k & 8) >> 1); return ((kk >> 3) * NC + (c >> 5)) * 512 + ((kk & 7) * 32 + (c & 31)) * 2; }
; __device__ __forceinline__ int v_rd_base(int lane) { return ((lane & 3) << 3) | (((lane >> 2) & 3) << 6) | (((lane >> 4) & 1) << 5) | (((lane >> 5) & 1) << 8); }
; #define SLOADX(S, k0) do { sk##S = *reinterpret_cast<const bf16x8*>(Kh + (long)(k0) * LD + kgo); sva##S = *reinterpret_cast<const bf16x8*>(Vh + (long)(k0) * LD + vgo); \
;     if constexpr (DV == 128) svb##S = *reinterpret_cast<const bf16x8*>(Vh + (long)((k0) + 32) * LD + vgo); } while (0)
; template <int DV, bool NA>
; __device__ __forceinline__ void attn_core(const bf16_t* __restrict__ Qlane, const bf16_t* __restrict__ Kh, const bf16_t* __restrict__ Vh, const int NT,
;                                           ALAS char* lds, f32x16 (&o)[DV / 32], const NaCtx& na) {
;     ...
;   int tid_ = threadIdx.x; asm volatile("" : "+v"(tid_));
;   const int tid = tid_, wid = __builtin_amdgcn_readfirstlane(tid >> 6), lane = tid & 63, r32 = lane & 31, hi = lane >> 5;
;   ALAS char* V_lds = lds + L_V; ALAS char* K_lds = lds + L_K;
;   ALAS float* al_l = (ALAS float*)(lds + L_WS) + wid * 64;
;   float m_ref = 0.f;
;   f32x16 osum = f32x16{}, negm = f32x16{};
; #pragma unroll
;   for (int d = 0; d < NC; ++d) o[d] = f32x16{};
;   bf16x8 qr[4];
; #pragma unroll
;   for (int d0 = 0; d0 < 4; ++d0) qr[d0] = *reinterpret_cast<const bf16x8*>(Qlane + d0 * 16);
;   const bf16x8 ones = {0x3f80, 0x3f80, 0x3f80, 0x3f80, 0x3f80, 0x3f80, 0x3f80, 0x3f80};
;   const int kr_ = tid >> 3, kc8 = (tid & 7) * 8, kst = KSWZ(kr_, kc8 * 2);
;   const int vr_ = (DV == 128) ? (tid >> 4) : (tid >> 3), vc8 = (DV == 128) ? (tid & 15) * 8 : (tid & 7) * 8;
;   const int vst0 = v_st<NC>(vr_, vc8), vst1 = v_st<NC>((32 + vr_) & 63, vc8);
;   const int vb0 = (int)(uintptr_t)V_lds + v_rd_base(lane);
;   const int kgo = kr_ * LD + kc8, vgo = vr_ * LD + vc8;
;   bf16x8 sk0, sva0, svb0, sk1, sva1, svb1;
;     ...
;   SLOADX(0, 0); asm volatile("s_waitcnt vmcnt(0)" ::: "memory"); SWRITEX(0, 0); SLOADX(1, 64); SLOADX(0, 128); __syncthreads();
.LBB0_248:
	v_mov_b32_e32 v1, v228
	s_lshl_b64 s[50:51], s[36:37], 1
	v_ashrrev_i32_e32 v22, 3, v1
	v_lshlrev_b32_e32 v30, 3, v1
	v_and_b32_e32 v23, 56, v30
	v_ashrrev_i32_e32 v31, 4, v1
	v_mul_lo_u32 v2, v22, s0
	v_or_b32_e32 v2, v2, v23
	v_mul_lo_u32 v3, v31, s0
	s_add_u32 s34, s20, s50
	v_and_or_b32 v4, v30, s33, v3
	v_lshrrev_b32_e32 v5, 3, v1
	v_mul_lo_u32 v2, v5, s0
	v_bfe_u32 v5, v1, 4, 3
	v_and_b32_e32 v6, 7, v1
	v_xor_b32_e32 v5, v5, v6
	v_lshl_or_b32 v2, v5, 3, v2
	v_bfe_u32 v5, v1, 2, 2
	v_bfe_u32 v6, v1, 7, 1
	v_lshl_or_b32 v5, v6, 2, v5
	v_bfe_u32 v6, v1, 4, 1
	v_lshl_or_b32 v5, v6, 3, v5
	v_bfe_u32 v6, v1, 8, 1
	v_lshl_or_b32 v5, v6, 4, v5
	v_mul_lo_u32 v4, v5, s0
	v_bfe_u32 v5, v1, 5, 2
	v_lshl_or_b32 v4, v5, 5, v4
	v_and_b32_e32 v5, 3, v1
	v_lshl_or_b32 v4, v5, 3, v4
	v_ashrrev_i32_e32 v3, 31, v2
	s_addc_u32 s35, s21, s51
	v_lshlrev_b64 v[14:15], 1, v[2:3]
	v_lshl_add_u64 v[16:17], s[34:35], 0, v[14:15]
	v_ashrrev_i32_e32 v5, 31, v4
	s_mov_b32 s34, 0x30000
	v_lshlrev_b64 v[18:19], 1, v[4:5]
	v_add_co_u32_e32 v28, vcc, s34, v16
	v_lshl_add_u64 v[2:3], s[20:21], 0, v[18:19]
	v_lshl_add_u64 v[6:7], s[26:27], 0, v[18:19]
	v_lshl_add_u64 v[20:21], v[208:209], 0, s[50:51]
	v_addc_co_u32_e32 v29, vcc, 0, v17, vcc
	v_readfirstlane_b32 s98, v1
	s_nop 0
	s_lshr_b32 s98, s98, 6
	s_lshl_b32 s98, s98, 10
	s_add_u32 s100, s20, 0x800
	s_addc_u32 s101, s21, 0
	v_lshl_add_u64 v[2:3], s[100:101], 0, v[18:19]
	s_mov_b32 m0, s98
	s_nop 0
	global_load_lds_dwordx4 v[2:3], off
	s_add_i32 m0, s98, 0x2000
	s_nop 0
	global_load_lds_dwordx4 v[6:7], off
	s_movk_i32 s100, 0x400
	s_mov_b32 s101, 0
	v_lshl_add_u64 v[10:11], v[16:17], 0, s[100:101]
	s_add_i32 m0, s98, 0x8000
	s_nop 0
	global_load_lds_dwordx4 v[10:11], off
	global_load_dwordx4 v[160:163], v[20:21], off
	global_load_dwordx4 v[164:167], v[20:21], off offset:32
	global_load_dwordx4 v[168:171], v[20:21], off offset:64
	global_load_dwordx4 v[172:175], v[20:21], off offset:96
	v_lshlrev_b32_e32 v20, 4, v1
	v_lshlrev_b32_e32 v21, 1, v1
	v_lshlrev_b32_e32 v35, 7, v22
	v_lshlrev_b32_e32 v22, 1, v31
	v_lshrrev_b32_e32 v24, 1, v31
	v_and_b32_e32 v25, 3, v31
	s_waitcnt vmcnt(0)
	v_add_co_u32_e32 v16, vcc, s24, v16
	v_and_b32_e32 v37, 48, v20
	v_and_b32_e32 v38, 0xc0, v20
	v_and_b32_e32 v39, 32, v21
	v_lshlrev_b32_e32 v40, 1, v23
	v_and_b32_e32 v41, 8, v22
	v_and_or_b32 v42, v24, 4, v25
	v_lshl_add_u64 v[20:21], s[38:39], 0, v[18:19]
	v_lshl_add_u64 v[22:23], s[40:41], 0, v[18:19]
	v_lshl_add_u64 v[24:25], s[42:43], 0, v[18:19]
	v_lshl_add_u64 v[26:27], s[44:45], 0, v[18:19]
	v_addc_co_u32_e32 v17, vcc, 0, v17, vcc
	s_mov_b32 s34, 0xfffff0
	v_and_b32_e32 v34, 0x70, v1
	v_and_or_b32 v17, v31, s34, v41
	v_and_or_b32 v21, v31, 48, v41
	v_bfe_u32 v36, v30, 5, 2
	v_bitop3_b32 v16, v40, v35, v34 bitop3:0xde
	v_lshrrev_b32_e32 v17, 1, v17
	v_lshrrev_b32_e32 v21, 1, v21
	v_readfirstlane_b32 s22, v1
	v_lshlrev_b32_e32 v20, 6, v42
	v_add_u32_e32 v217, 0, v16
	v_or_b32_e32 v16, v17, v36
	v_or_b32_e32 v17, v21, v36
	v_and_b32_e32 v32, 31, v1
	v_and_b32_e32 v33, 63, v1
	v_lshrrev_b32_e32 v1, 1, v1
	s_and_b32 s22, s22, 0x3fffffc0
	v_lshl_or_b32 v17, v17, 9, v20
	s_movk_i32 s34, 0x2000
	s_lshl_b32 s22, s22, 2
	v_bitop3_b32 v17, v17, s34, v37 bitop3:0x36
	v_and_b32_e32 v220, 16, v1
	s_movk_i32 s34, 0x70
	s_add_i32 s22, s22, 0
	v_add_u32_e32 v219, 0, v17
	v_and_b32_e32 v1, 0x70, v30
	v_bitop3_b32 v17, v30, v220, s34 bitop3:0x6c
	s_movk_i32 s34, 0x60
	v_lshlrev_b32_e32 v16, 9, v16
	v_bitop3_b32 v22, v220, v1, s34 bitop3:0x36
	s_add_u32 s34, s46, s50
	v_or3_b32 v16, v16, v20, v37
	s_addc_u32 s35, s47, s51
	v_add_u32_e32 v218, 0, v16
	v_lshl_add_u32 v16, v32, 7, 0
	v_bitop3_b32 v20, v220, v1, 32 bitop3:0x36
	v_bitop3_b32 v21, v220, v1, 64 bitop3:0x36
	v_and_or_b32 v1, v30, s3, v39
	v_lshl_add_u64 v[212:213], s[34:35], 0, v[14:15]
	v_mov_b32_e32 v14, v0
	v_mov_b32_e32 v15, v0
	v_cmp_gt_u32_e64 s[36:37], 32, v33
	v_lshl_add_u32 v221, v32, 2, s22
	v_add3_u32 v222, v38, 0, v1
	v_lshl_add_u64 v[210:211], s[46:47], 0, v[18:19]
	v_mov_b32_e32 v1, v0
	v_mov_b32_e32 v2, v0
	v_mov_b32_e32 v3, v0
	v_mov_b32_e32 v4, v0
	v_mov_b32_e32 v5, v0
	v_mov_b32_e32 v6, v0
	v_mov_b32_e32 v7, v0
	v_mov_b32_e32 v8, v0
	v_mov_b32_e32 v9, v0
	v_mov_b32_e32 v10, v0
	v_mov_b32_e32 v11, v0
	v_mov_b32_e32 v12, v0
	v_mov_b32_e32 v13, v0
	v_mov_b32_e32 v224, 0
	v_add_u32_e32 v225, v16, v17
	v_add_u32_e32 v226, v16, v20
	v_add_u32_e32 v227, v16, v21
	v_add_u32_e32 v236, v16, v22
	v_mov_b64_e32 v[78:79], v[14:15]
	v_mov_b64_e32 v[62:63], v[14:15]
	v_mov_b64_e32 v[46:47], v[14:15]
	v_mov_b64_e32 v[30:31], v[14:15]
	v_mov_b64_e32 v[94:95], v[14:15]
	v_add_u32_e32 v223, 0x4000, v222
	s_mov_b32 s59, -2
	v_mov_b64_e32 v[76:77], v[12:13]
	v_mov_b64_e32 v[74:75], v[10:11]
	v_mov_b64_e32 v[72:73], v[8:9]
	v_mov_b64_e32 v[70:71], v[6:7]
	v_mov_b64_e32 v[68:69], v[4:5]
	v_mov_b64_e32 v[66:67], v[2:3]
	v_mov_b64_e32 v[64:65], v[0:1]
	v_mov_b64_e32 v[60:61], v[12:13]
	v_mov_b64_e32 v[58:59], v[10:11]
	v_mov_b64_e32 v[56:57], v[8:9]
	v_mov_b64_e32 v[54:55], v[6:7]
	v_mov_b64_e32 v[52:53], v[4:5]
	v_mov_b64_e32 v[50:51], v[2:3]
	v_mov_b64_e32 v[48:49], v[0:1]
	v_mov_b64_e32 v[44:45], v[12:13]
	v_mov_b64_e32 v[42:43], v[10:11]
	v_mov_b64_e32 v[40:41], v[8:9]
	v_mov_b64_e32 v[38:39], v[6:7]
	v_mov_b64_e32 v[36:37], v[4:5]
	v_mov_b64_e32 v[34:35], v[2:3]
	v_mov_b64_e32 v[32:33], v[0:1]
	v_mov_b64_e32 v[28:29], v[12:13]
	v_mov_b64_e32 v[26:27], v[10:11]
	v_mov_b64_e32 v[24:25], v[8:9]
	v_mov_b64_e32 v[22:23], v[6:7]
	v_mov_b64_e32 v[20:21], v[4:5]
	v_mov_b64_e32 v[18:19], v[2:3]
	v_mov_b64_e32 v[16:17], v[0:1]
	v_mov_b64_e32 v[92:93], v[12:13]
	v_mov_b64_e32 v[90:91], v[10:11]
	v_mov_b64_e32 v[88:89], v[8:9]
	v_mov_b64_e32 v[86:87], v[6:7]
	v_mov_b64_e32 v[84:85], v[4:5]
	v_mov_b64_e32 v[82:83], v[2:3]
	v_mov_b64_e32 v[80:81], v[0:1]
	v_mov_b32_e32 v112, 0
	v_mov_b32_e32 v113, v224
	v_mov_b32_e32 v114, v224
	v_mov_b32_e32 v115, v224
	v_mov_b32_e32 v116, v224
	v_mov_b32_e32 v117, v224
	v_mov_b32_e32 v118, v224
	v_mov_b32_e32 v119, v224
	v_mov_b32_e32 v120, v224
	v_mov_b32_e32 v121, v224
	v_mov_b32_e32 v122, v224
	v_mov_b32_e32 v123, v224
	v_mov_b32_e32 v124, v224
	v_mov_b32_e32 v125, v224
	v_mov_b32_e32 v126, v224
	v_mov_b32_e32 v127, v224
	s_waitcnt lgkmcnt(0)
	s_barrier
; #define SLOADX(S, k0) do { sk##S = *reinterpret_cast<const bf16x8*>(Kh + (long)(k0) * LD + kgo); sva##S = *reinterpret_cast<const bf16x8*>(Vh + (long)(k0) * LD + vgo); \
;     if constexpr (DV == 128) svb##S = *reinterpret_cast<const bf16x8*>(Vh + (long)((k0) + 32) * LD + vgo); } while (0)
; #define SWRITEX(S, b) do { *(ALAS bf16x8*)(V_lds + (b) * SHM_V + vst0) = sva##S; if constexpr (DV == 128) *(ALAS bf16x8*)(V_lds + (b) * SHM_V + vst1) = svb##S; \
;     *(ALAS bf16x8*)(K_lds + (b) * SHM_K + kst) = sk##S; } while (0)
; template <int DV, bool NA>
; __device__ __forceinline__ void attn_core(const bf16_t* __restrict__ Qlane, const bf16_t* __restrict__ Kh, const bf16_t* __restrict__ Vh, const int NT,
;                                           ALAS char* lds, f32x16 (&o)[DV / 32], const NaCtx& na) {
;     ...
;   for (int jj = 0; jj < NT; jj += 2) {
; #pragma unroll
;    for (int par = 0; par < 2; ++par) {
;     const int j = jj + par; const int b = par; const bool act = ACT(j);
;     bf16x8 kf[8];
;     if (act) k_issue(kf, K_lds + b * SHM_K, r32, hi);
;     if (par == 0) { if (j + 1 < NT) { SWRITEX(1, 1); if (j + 3 < NT) SLOADX(1, (j + 3) * 64); } }
;     else          { if (j + 1 < NT) { SWRITEX(0, 0); if (j + 3 < NT) SLOADX(0, (j + 3) * 64); } }
;     if (act) {
;       f32x16 p0, p1;
;       qkt(p0, p1, kf, qr, negm);
;       if constexpr (NA) na_bias(p0, p1, j, hi, na);
;       float pmax = fmaxf(p0[0], p1[0]), pmx2 = fmaxf(p0[1], p1[1]);
; #pragma unroll
;       for (int r = 2; r < 16; r += 2) { pmax = __builtin_fmaxf(__builtin_fmaxf(pmax, p0[r]), p1[r]); pmx2 = __builtin_fmaxf(__builtin_fmaxf(pmx2, p0[r + 1]), p1[r + 1]); }
;       pmax = fmaxf(pmax, pmx2);
;       { auto rr = __builtin_amdgcn_permlane32_swap(__float_as_uint(pmax), __float_as_uint(pmax), false, false);
;         pmax = fmaxf(__uint_as_float(rr[0]), __uint_as_float(rr[1])); }
;       if (__builtin_expect(!__all(pmax <= THR2), 0)) {
.LBB0_249:
	ds_read_b128 v[128:131], v225 offset:32768
	ds_read_b128 v[108:111], v225 offset:36864
	ds_read_b128 v[104:107], v226 offset:32768
	ds_read_b128 v[100:103], v226 offset:36864
	ds_read_b128 v[96:99], v227 offset:32768
	ds_read_b128 v[10:13], v227 offset:36864
	ds_read_b128 v[2:5], v236 offset:32768
	ds_read_b128 v[6:9], v236 offset:36864
	s_add_i32 s58, s59, 2
	v_lshl_add_u64 v[14:15], v[212:213], 0, s[6:7]
	v_add_co_u32_e32 v14, vcc, 0x1f830400, v14
	s_add_i32 m0, s98, 0xa000
	s_nop 0
	v_addc_co_u32_e32 v15, vcc, 0, v15, vcc
	global_load_lds_dwordx4 v[14:15], off
	v_lshl_add_u64 v[14:15], v[210:211], 0, s[6:7]
	v_add_co_u32_e32 v132, vcc, 0x1f830800, v14
	s_add_i32 m0, s98, 0x4000
	s_nop 0
	v_addc_co_u32_e32 v133, vcc, 0, v15, vcc
	v_add_co_u32_e32 v14, vcc, 0x1f848800, v14
	global_load_lds_dwordx4 v[132:133], off
	s_add_i32 m0, s98, 0x6000
	s_nop 0
	v_addc_co_u32_e32 v15, vcc, 0, v15, vcc
	global_load_lds_dwordx4 v[14:15], off
.LBB0_251:
	s_waitcnt lgkmcnt(7)
	v_mfma_f32_32x32x16_bf16 v[144:159], v[128:131], v[160:163], v[112:127]
	s_waitcnt lgkmcnt(5)
	v_mfma_f32_32x32x16_bf16 v[144:159], v[104:107], v[164:167], v[144:159]
	v_mfma_f32_32x32x16_bf16 v[128:143], v[108:111], v[160:163], v[112:127]
	s_waitcnt lgkmcnt(4)
	v_mfma_f32_32x32x16_bf16 v[128:143], v[100:103], v[164:167], v[128:143]
	s_waitcnt lgkmcnt(3)
	v_mfma_f32_32x32x16_bf16 v[144:159], v[96:99], v[168:171], v[144:159]
	s_waitcnt lgkmcnt(2)
	v_mfma_f32_32x32x16_bf16 v[128:143], v[10:13], v[168:171], v[128:143]
	s_waitcnt lgkmcnt(0)
	v_mfma_f32_32x32x16_bf16 v[128:143], v[6:9], v[172:175], v[128:143]
	v_mfma_f32_32x32x16_bf16 v[144:159], v[2:5], v[172:175], v[144:159]
	s_nop 10
	v_max_f32_e32 v1, v145, v129
	v_max3_f32 v2, v144, v128, v146
	v_max3_f32 v1, v1, v147, v131
	v_max3_f32 v2, v2, v130, v148
	v_max3_f32 v1, v1, v149, v133
	v_max3_f32 v2, v2, v132, v150
	v_max3_f32 v1, v1, v151, v135
	v_max3_f32 v2, v2, v134, v152
	v_max3_f32 v1, v1, v153, v137
	v_max3_f32 v2, v2, v136, v154
	v_max3_f32 v1, v1, v155, v139
	v_max3_f32 v2, v2, v138, v156
	v_max3_f32 v1, v1, v157, v141
	v_max3_f32 v2, v2, v140, v158
	v_max3_f32 v1, v1, v159, v143
	v_max3_f32 v1, v2, v142, v1
	v_mov_b32_e32 v2, v1
	s_nop 1
	v_permlane32_swap_b32_e32 v1, v2
	v_max_f32_e32 v1, v1, v2
	v_cmp_ge_f32_e32 vcc, s2, v1
	s_cmp_eq_u64 vcc, exec
	s_cbranch_scc0 .LBB0_259
; #define SBAR() __builtin_amdgcn_sched_barrier(0)
; #define SLOADX(S, k0) do { sk##S = *reinterpret_cast<const bf16x8*>(Kh + (long)(k0) * LD + kgo); sva##S = *reinterpret_cast<const bf16x8*>(Vh + (long)(k0) * LD + vgo); \
;     if constexpr (DV == 128) svb##S = *reinterpret_cast<const bf16x8*>(Vh + (long)((k0) + 32) * LD + vgo); } while (0)
; #define SWRITEX(S, b) do { *(ALAS bf16x8*)(V_lds + (b) * SHM_V + vst0) = sva##S; if constexpr (DV == 128) *(ALAS bf16x8*)(V_lds + (b) * SHM_V + vst1) = svb##S; \
;     *(ALAS bf16x8*)(K_lds + (b) * SHM_K + kst) = sk##S; } while (0)
; #define EXP8(P, BASE) do { _Pragma("unroll") for (int r = 0; r < 8; ++r) P[BASE + r] = __builtin_amdgcn_exp2f(P[BASE + r]); } while (0)
; #define LGKM(n) asm volatile("s_waitcnt lgkmcnt(" #n ")" ::: "memory")
; template <int DV, bool NA>
; __device__ __forceinline__ void attn_core(const bf16_t* __restrict__ Qlane, const bf16_t* __restrict__ Kh, const bf16_t* __restrict__ Vh, const int NT,
;                                           ALAS char* lds, f32x16 (&o)[DV / 32], const NaCtx& na) {
;     ...
;     const int j = jj + par; const int b = par; const bool act = ACT(j);
;     bf16x8 kf[8];
;     if (act) k_issue(kf, K_lds + b * SHM_K, r32, hi);
;     if (par == 0) { if (j + 1 < NT) { SWRITEX(1, 1); if (j + 3 < NT) SLOADX(1, (j + 3) * 64); } }
;     else          { if (j + 1 < NT) { SWRITEX(0, 0); if (j + 3 < NT) SLOADX(0, (j + 3) * 64); } }
;     ...
;       const int vb = vb0 + b * SHM_V;
;       s16x4 LA[8], LB[8]; bf16x8 pa;
;     ...
;       v_issue_k<NC, 0>(LA, vb);
;       EXP8(p0, 0); PK4(p0, 0, pa); SBAR();
;       v_issue_k<NC, 1>(LB, vb); if constexpr (NC == 4) LGKM(8); else LGKM(4); SBAR(); v_mma_k<NC>(o, osum, LA, pa, ones); SBAR();
;       EXP8(p0, 8); PK4(p0, 8, pa); SBAR();
;       v_issue_k<NC, 2>(LA, vb); if constexpr (NC == 4) LGKM(8); else LGKM(4); SBAR(); v_mma_k<NC>(o, osum, LB, pa, ones); SBAR();
;       EXP8(p1, 0); PK4(p1, 0, pa); SBAR();
;       v_issue_k<NC, 3>(LB, vb); if constexpr (NC == 4) LGKM(8); else LGKM(4); SBAR(); v_mma_k<NC>(o, osum, LA, pa, ones); SBAR();
;       EXP8(p1, 8); PK4(p1, 8, pa); SBAR();
;       LGKM(0); SBAR(); v_mma_k<NC>(o, osum, LB, pa, ones);
;     ...
;     }
;     __syncthreads();
.LBB0_253:
	ds_read_b64_tr_b16 v[2:3], v222 offset:0
	ds_read_b64_tr_b16 v[4:5], v222 offset:0x800
	ds_read_b64_tr_b16 v[6:7], v222 offset:0x200
	ds_read_b64_tr_b16 v[8:9], v222 offset:0xa00
	ds_read_b64_tr_b16 v[10:11], v222 offset:0x400
	v_exp_f32_e32 v1, v144
	v_exp_f32_e32 v14, v145
	v_exp_f32_e32 v15, v146
	v_exp_f32_e32 v145, v147
	v_exp_f32_e32 v146, v148
	v_exp_f32_e32 v147, v149
	v_exp_f32_e32 v148, v150
	v_exp_f32_e32 v149, v151
	ds_read_b64_tr_b16 v[12:13], v222 offset:0xc00
	ds_read_b64_tr_b16 v[200:201], v222 offset:0x600
	ds_read_b64_tr_b16 v[202:203], v222 offset:0xe00
	v_cvt_pk_bf16_f32 v144, v1, v14
	v_cvt_pk_bf16_f32 v145, v15, v145
	v_cvt_pk_bf16_f32 v146, v146, v147
	v_cvt_pk_bf16_f32 v147, v148, v149
	s_nop 0
	v_permlane32_swap_b32_e32 v144, v146
	v_permlane32_swap_b32_e32 v145, v147
	s_add_i32 s50, s59, 3
	ds_read_b64_tr_b16 v[148:149], v222 offset:0x1000
	ds_read_b64_tr_b16 v[150:151], v222 offset:0x1800
	ds_read_b64_tr_b16 v[238:239], v222 offset:0x1200
	ds_read_b64_tr_b16 v[240:241], v222 offset:0x1a00
	ds_read_b64_tr_b16 v[242:243], v222 offset:0x1400
	ds_read_b64_tr_b16 v[244:245], v222 offset:0x1c00
	ds_read_b64_tr_b16 v[246:247], v222 offset:0x1600
	ds_read_b64_tr_b16 v[248:249], v222 offset:0x1e00
	s_waitcnt lgkmcnt(8)
	v_mfma_f32_32x32x16_bf16 v[64:79], v[144:147], v[2:5], v[64:79]
	v_mfma_f32_32x32x16_bf16 v[48:63], v[144:147], v[6:9], v[48:63]
	v_mfma_f32_32x32x16_bf16 v[32:47], v[144:147], v[10:13], v[32:47]
	v_mfma_f32_32x32x16_bf16 v[16:31], v[144:147], v[200:203], v[16:31]
	v_exp_f32_e32 v1, v152
	v_exp_f32_e32 v2, v153
	v_exp_f32_e32 v3, v154
	v_exp_f32_e32 v4, v155
	v_exp_f32_e32 v5, v156
	v_exp_f32_e32 v6, v157
	v_exp_f32_e32 v7, v158
	v_exp_f32_e32 v8, v159
	v_cvt_pk_bf16_f32 v2, v1, v2
	v_cvt_pk_bf16_f32 v3, v3, v4
	v_cvt_pk_bf16_f32 v4, v5, v6
	v_cvt_pk_bf16_f32 v5, v7, v8
	s_nop 0
	v_permlane32_swap_b32_e32 v2, v4
	v_permlane32_swap_b32_e32 v3, v5
	ds_read_b64_tr_b16 v[6:7], v222 offset:0x2000
	ds_read_b64_tr_b16 v[8:9], v222 offset:0x2800
	ds_read_b64_tr_b16 v[10:11], v222 offset:0x2200
	ds_read_b64_tr_b16 v[12:13], v222 offset:0x2a00
	ds_read_b64_tr_b16 v[152:153], v222 offset:0x2400
	ds_read_b64_tr_b16 v[154:155], v222 offset:0x2c00
	ds_read_b64_tr_b16 v[156:157], v222 offset:0x2600
	ds_read_b64_tr_b16 v[158:159], v222 offset:0x2e00
	s_waitcnt lgkmcnt(8)
	v_mfma_f32_32x32x16_bf16 v[64:79], v[2:5], v[148:151], v[64:79]
	v_mfma_f32_32x32x16_bf16 v[48:63], v[2:5], v[238:241], v[48:63]
	v_mfma_f32_32x32x16_bf16 v[32:47], v[2:5], v[242:245], v[32:47]
	v_mfma_f32_32x32x16_bf16 v[16:31], v[2:5], v[246:249], v[16:31]
	v_exp_f32_e32 v1, v128
	v_exp_f32_e32 v14, v129
	v_exp_f32_e32 v15, v130
	v_exp_f32_e32 v148, v131
	v_mov_b64_e32 v[130:131], s[10:11]
	v_mov_b64_e32 v[128:129], s[8:9]
	v_exp_f32_e32 v149, v132
	v_exp_f32_e32 v150, v133
	v_mfma_f32_32x32x16_bf16 v[80:95], v[144:147], v[128:131], v[80:95]
	v_exp_f32_e32 v151, v134
	v_exp_f32_e32 v135, v135
	v_cvt_pk_bf16_f32 v132, v1, v14
	v_cvt_pk_bf16_f32 v133, v15, v148
	v_cvt_pk_bf16_f32 v134, v149, v150
	v_cvt_pk_bf16_f32 v135, v151, v135
	s_nop 0
	v_permlane32_swap_b32_e32 v132, v134
	v_permlane32_swap_b32_e32 v133, v135
	ds_read_b64_tr_b16 v[144:145], v222 offset:0x3000
	ds_read_b64_tr_b16 v[146:147], v222 offset:0x3800
	ds_read_b64_tr_b16 v[148:149], v222 offset:0x3200
	ds_read_b64_tr_b16 v[150:151], v222 offset:0x3a00
	ds_read_b64_tr_b16 v[200:201], v222 offset:0x3400
	ds_read_b64_tr_b16 v[202:203], v222 offset:0x3c00
	ds_read_b64_tr_b16 v[238:239], v222 offset:0x3600
	ds_read_b64_tr_b16 v[240:241], v222 offset:0x3e00
	s_waitcnt lgkmcnt(8)
	v_mfma_f32_32x32x16_bf16 v[64:79], v[132:135], v[6:9], v[64:79]
	v_mfma_f32_32x32x16_bf16 v[48:63], v[132:135], v[10:13], v[48:63]
	v_mfma_f32_32x32x16_bf16 v[32:47], v[132:135], v[152:155], v[32:47]
	v_mfma_f32_32x32x16_bf16 v[16:31], v[132:135], v[156:159], v[16:31]
	v_mfma_f32_32x32x16_bf16 v[80:95], v[2:5], v[128:131], v[80:95]
	v_exp_f32_e32 v1, v136
	v_exp_f32_e32 v6, v137
	v_exp_f32_e32 v7, v138
	v_exp_f32_e32 v8, v139
	v_exp_f32_e32 v9, v140
	v_exp_f32_e32 v4, v141
	v_exp_f32_e32 v5, v142
	v_mfma_f32_32x32x16_bf16 v[80:95], v[132:135], v[128:131], v[80:95]
	v_exp_f32_e32 v10, v143
	v_cvt_pk_bf16_f32 v2, v1, v6
	v_cvt_pk_bf16_f32 v3, v7, v8
	v_cvt_pk_bf16_f32 v4, v9, v4
	v_cvt_pk_bf16_f32 v5, v5, v10
	s_nop 0
	v_permlane32_swap_b32_e32 v2, v4
	v_permlane32_swap_b32_e32 v3, v5
	s_waitcnt lgkmcnt(0)
	s_nop 1
	v_mfma_f32_32x32x16_bf16 v[80:95], v[2:5], v[128:131], v[80:95]
	s_waitcnt lgkmcnt(0)
	s_waitcnt vmcnt(0)
	s_barrier
	s_cmp_gt_u32 s50, 62
	v_mfma_f32_32x32x16_bf16 v[64:79], v[2:5], v[144:147], v[64:79]
	v_mfma_f32_32x32x16_bf16 v[48:63], v[2:5], v[148:151], v[48:63]
	v_mfma_f32_32x32x16_bf16 v[32:47], v[2:5], v[200:203], v[32:47]
	v_mfma_f32_32x32x16_bf16 v[16:31], v[2:5], v[238:241], v[16:31]
	ds_read_b128 v[156:159], v225 offset:40960
	ds_read_b128 v[200:203], v225 offset:45056
	ds_read_b128 v[152:155], v226 offset:40960
	ds_read_b128 v[148:151], v226 offset:45056
	ds_read_b128 v[144:147], v227 offset:40960
	ds_read_b128 v[10:13], v227 offset:45056
	ds_read_b128 v[2:5], v236 offset:40960
	ds_read_b128 v[6:9], v236 offset:45056
	s_cbranch_scc1 .LBB0_256
	v_lshl_add_u64 v[14:15], v[212:213], 0, s[6:7]
	v_add_co_u32_e32 v14, vcc, 0x1f860400, v14
	s_add_i32 m0, s98, 0x8000
	s_nop 0
	v_addc_co_u32_e32 v15, vcc, 0, v15, vcc
	global_load_lds_dwordx4 v[14:15], off
	v_lshl_add_u64 v[14:15], v[210:211], 0, s[6:7]
	v_add_co_u32_e32 v128, vcc, 0x1f860800, v14
	s_mov_b32 m0, s98
	s_nop 0
	v_addc_co_u32_e32 v129, vcc, 0, v15, vcc
	v_add_co_u32_e32 v14, vcc, 0x1f878800, v14
	global_load_lds_dwordx4 v[128:129], off
	s_add_i32 m0, s98, 0x2000
	s_nop 0
	v_addc_co_u32_e32 v15, vcc, 0, v15, vcc
	global_load_lds_dwordx4 v[14:15], off

; #define SBAR() __builtin_amdgcn_sched_barrier(0)
; #define EXP8(P, BASE) do { _Pragma("unroll") for (int r = 0; r < 8; ++r) P[BASE + r] = __builtin_amdgcn_exp2f(P[BASE + r]); } while (0)
; #define LGKM(n) asm volatile("s_waitcnt lgkmcnt(" #n ")" ::: "memory")
; template <int DV, bool NA>
; __device__ __forceinline__ void attn_core(const bf16_t* __restrict__ Qlane, const bf16_t* __restrict__ Kh, const bf16_t* __restrict__ Vh, const int NT,
;                                           ALAS char* lds, f32x16 (&o)[DV / 32], const NaCtx& na) {
;     ...
;       const int vb = vb0 + b * SHM_V;
;       s16x4 LA[8], LB[8]; bf16x8 pa;
;     ...
;       v_issue_k<NC, 0>(LA, vb);
;       EXP8(p0, 0); PK4(p0, 0, pa); SBAR();
;       v_issue_k<NC, 1>(LB, vb); if constexpr (NC == 4) LGKM(8); else LGKM(4); SBAR(); v_mma_k<NC>(o, osum, LA, pa, ones); SBAR();
;       EXP8(p0, 8); PK4(p0, 8, pa); SBAR();
;       v_issue_k<NC, 2>(LA, vb); if constexpr (NC == 4) LGKM(8); else LGKM(4); SBAR(); v_mma_k<NC>(o, osum, LB, pa, ones); SBAR();
;       EXP8(p1, 0); PK4(p1, 0, pa); SBAR();
;       v_issue_k<NC, 3>(LB, vb); if constexpr (NC == 4) LGKM(8); else LGKM(4); SBAR(); v_mma_k<NC>(o, osum, LA, pa, ones); SBAR();
;       EXP8(p1, 8); PK4(p1, 8, pa); SBAR();
;       LGKM(0); SBAR(); v_mma_k<NC>(o, osum, LB, pa, ones);
;     ...
;     }
;     __syncthreads();
.LBB0_257:
	ds_read_b64_tr_b16 v[2:3], v223 offset:0
	ds_read_b64_tr_b16 v[4:5], v223 offset:0x800
	ds_read_b64_tr_b16 v[6:7], v223 offset:0x200
	ds_read_b64_tr_b16 v[8:9], v223 offset:0xa00
	ds_read_b64_tr_b16 v[10:11], v223 offset:0x400
	ds_read_b64_tr_b16 v[12:13], v223 offset:0xc00
	v_exp_f32_e32 v1, v128
	v_exp_f32_e32 v14, v129
	v_exp_f32_e32 v15, v130
	v_exp_f32_e32 v129, v131
	v_exp_f32_e32 v130, v132
	v_exp_f32_e32 v131, v133
	v_exp_f32_e32 v132, v134
	v_exp_f32_e32 v133, v135
	ds_read_b64_tr_b16 v[144:145], v223 offset:0x600
	ds_read_b64_tr_b16 v[146:147], v223 offset:0xe00
	v_cvt_pk_bf16_f32 v128, v1, v14
	v_cvt_pk_bf16_f32 v129, v15, v129
	v_cvt_pk_bf16_f32 v130, v130, v131
	v_cvt_pk_bf16_f32 v131, v132, v133
	s_nop 0
	v_permlane32_swap_b32_e32 v128, v130
	v_permlane32_swap_b32_e32 v129, v131
	ds_read_b64_tr_b16 v[132:133], v223 offset:0x1000
	ds_read_b64_tr_b16 v[134:135], v223 offset:0x1800
	ds_read_b64_tr_b16 v[148:149], v223 offset:0x1200
	ds_read_b64_tr_b16 v[150:151], v223 offset:0x1a00
	ds_read_b64_tr_b16 v[152:153], v223 offset:0x1400
	ds_read_b64_tr_b16 v[154:155], v223 offset:0x1c00
	ds_read_b64_tr_b16 v[156:157], v223 offset:0x1600
	ds_read_b64_tr_b16 v[158:159], v223 offset:0x1e00
	s_waitcnt lgkmcnt(8)
	v_mfma_f32_32x32x16_bf16 v[64:79], v[128:131], v[2:5], v[64:79]
	v_mfma_f32_32x32x16_bf16 v[48:63], v[128:131], v[6:9], v[48:63]
	v_mfma_f32_32x32x16_bf16 v[32:47], v[128:131], v[10:13], v[32:47]
	v_mfma_f32_32x32x16_bf16 v[16:31], v[128:131], v[144:147], v[16:31]
	v_exp_f32_e32 v1, v136
	v_exp_f32_e32 v2, v137
	v_exp_f32_e32 v3, v138
	v_exp_f32_e32 v4, v139
	v_exp_f32_e32 v5, v140
	v_exp_f32_e32 v6, v141
	v_exp_f32_e32 v7, v142
	v_exp_f32_e32 v8, v143
	v_cvt_pk_bf16_f32 v2, v1, v2
	v_cvt_pk_bf16_f32 v3, v3, v4
	v_cvt_pk_bf16_f32 v4, v5, v6
	v_cvt_pk_bf16_f32 v5, v7, v8
	s_nop 0
	v_permlane32_swap_b32_e32 v2, v4
	v_permlane32_swap_b32_e32 v3, v5
	ds_read_b64_tr_b16 v[6:7], v223 offset:0x2000
	ds_read_b64_tr_b16 v[8:9], v223 offset:0x2800
	ds_read_b64_tr_b16 v[10:11], v223 offset:0x2200
	ds_read_b64_tr_b16 v[12:13], v223 offset:0x2a00
	ds_read_b64_tr_b16 v[136:137], v223 offset:0x2400
	ds_read_b64_tr_b16 v[138:139], v223 offset:0x2c00
	ds_read_b64_tr_b16 v[140:141], v223 offset:0x2600
	ds_read_b64_tr_b16 v[142:143], v223 offset:0x2e00
	s_waitcnt lgkmcnt(8)
	v_mfma_f32_32x32x16_bf16 v[64:79], v[2:5], v[132:135], v[64:79]
	v_mfma_f32_32x32x16_bf16 v[48:63], v[2:5], v[148:151], v[48:63]
	v_mfma_f32_32x32x16_bf16 v[32:47], v[2:5], v[152:155], v[32:47]
	v_mfma_f32_32x32x16_bf16 v[16:31], v[2:5], v[156:159], v[16:31]
	v_exp_f32_e32 v1, v96
	v_exp_f32_e32 v14, v97
	v_exp_f32_e32 v15, v98
	v_exp_f32_e32 v132, v99
	v_mov_b64_e32 v[98:99], s[10:11]
	v_mov_b64_e32 v[96:97], s[8:9]
	v_exp_f32_e32 v133, v100
	v_exp_f32_e32 v134, v101
	v_mfma_f32_32x32x16_bf16 v[80:95], v[128:131], v[96:99], v[80:95]
	v_exp_f32_e32 v135, v102
	v_exp_f32_e32 v103, v103
	v_cvt_pk_bf16_f32 v100, v1, v14
	v_cvt_pk_bf16_f32 v101, v15, v132
	v_cvt_pk_bf16_f32 v102, v133, v134
	v_cvt_pk_bf16_f32 v103, v135, v103
	s_nop 0
	v_permlane32_swap_b32_e32 v100, v102
	v_permlane32_swap_b32_e32 v101, v103
	ds_read_b64_tr_b16 v[128:129], v223 offset:0x3000
	ds_read_b64_tr_b16 v[130:131], v223 offset:0x3800
	ds_read_b64_tr_b16 v[132:133], v223 offset:0x3200
	ds_read_b64_tr_b16 v[134:135], v223 offset:0x3a00
	ds_read_b64_tr_b16 v[144:145], v223 offset:0x3400
	ds_read_b64_tr_b16 v[146:147], v223 offset:0x3c00
	ds_read_b64_tr_b16 v[148:149], v223 offset:0x3600
	ds_read_b64_tr_b16 v[150:151], v223 offset:0x3e00
	s_waitcnt lgkmcnt(8)
	v_mfma_f32_32x32x16_bf16 v[64:79], v[100:103], v[6:9], v[64:79]
	v_mfma_f32_32x32x16_bf16 v[48:63], v[100:103], v[10:13], v[48:63]
	v_mfma_f32_32x32x16_bf16 v[32:47], v[100:103], v[136:139], v[32:47]
	v_mfma_f32_32x32x16_bf16 v[16:31], v[100:103], v[140:143], v[16:31]
	v_mfma_f32_32x32x16_bf16 v[80:95], v[2:5], v[96:99], v[80:95]
	v_exp_f32_e32 v1, v104
	v_exp_f32_e32 v6, v105
	v_exp_f32_e32 v7, v106
	v_exp_f32_e32 v8, v107
	v_exp_f32_e32 v9, v108
	v_exp_f32_e32 v4, v109
	v_exp_f32_e32 v5, v110
	v_mfma_f32_32x32x16_bf16 v[80:95], v[100:103], v[96:99], v[80:95]
	v_exp_f32_e32 v10, v111
	v_cvt_pk_bf16_f32 v2, v1, v6
	v_cvt_pk_bf16_f32 v3, v7, v8
	v_cvt_pk_bf16_f32 v4, v9, v4
	v_cvt_pk_bf16_f32 v5, v5, v10
	s_nop 0
	v_permlane32_swap_b32_e32 v2, v4
	v_permlane32_swap_b32_e32 v3, v5
	s_waitcnt lgkmcnt(0)
	s_nop 1
	v_mfma_f32_32x32x16_bf16 v[80:95], v[2:5], v[96:99], v[80:95]
	v_lshl_add_u64 v[210:211], v[210:211], 0, s[18:19]
	v_lshl_add_u64 v[212:213], v[212:213], 0, s[18:19]
	s_cmp_lt_u32 s58, 62
	s_waitcnt vmcnt(0)
	s_barrier
	v_mfma_f32_32x32x16_bf16 v[64:79], v[2:5], v[128:131], v[64:79]
	v_mfma_f32_32x32x16_bf16 v[48:63], v[2:5], v[132:135], v[48:63]
	v_mfma_f32_32x32x16_bf16 v[32:47], v[2:5], v[144:147], v[32:47]
	v_mfma_f32_32x32x16_bf16 v[16:31], v[2:5], v[148:151], v[16:31]
	s_cbranch_scc0 .LBB0_265
	s_mov_b32 s59, s58
	s_branch .LBB0_249

; #define ALAS __attribute__((address_space(3)))
; template <int NC> __device__ __forceinline__ int v_st(int k, int c) { const int kk = (k & ~0xC) | ((k & 4) << 1) | ((k & 8) >> 1); return ((kk >> 3) * NC + (c >> 5)) * 512 + ((kk & 7) * 32 + (c & 31)) * 2; }
; __device__ __forceinline__ int v_rd_base(int lane) { return ((lane & 3) << 3) | (((lane >> 2) & 3) << 6) | (((lane >> 4) & 1) << 5) | (((lane >> 5) & 1) << 8); }
; template <int DV, bool NA>
; __device__ __forceinline__ void attn_core(const bf16_t* __restrict__ Qlane, const bf16_t* __restrict__ Kh, const bf16_t* __restrict__ Vh, const int NT,
;                                           ALAS char* lds, f32x16 (&o)[DV / 32], const NaCtx& na) {
;     ...
;   int tid_ = threadIdx.x; asm volatile("" : "+v"(tid_));
;   const int tid = tid_, wid = __builtin_amdgcn_readfirstlane(tid >> 6), lane = tid & 63, r32 = lane & 31, hi = lane >> 5;
;   ALAS char* V_lds = lds + L_V; ALAS char* K_lds = lds + L_K;
;   ALAS float* al_l = (ALAS float*)(lds + L_WS) + wid * 64;
;   float m_ref = 0.f;
;   f32x16 osum = f32x16{}, negm = f32x16{};
; #pragma unroll
;   for (int d = 0; d < NC; ++d) o[d] = f32x16{};
;   bf16x8 qr[4];
; #pragma unroll
;   for (int d0 = 0; d0 < 4; ++d0) qr[d0] = *reinterpret_cast<const bf16x8*>(Qlane + d0 * 16);
;   const bf16x8 ones = {0x3f80, 0x3f80, 0x3f80, 0x3f80, 0x3f80, 0x3f80, 0x3f80, 0x3f80};
;   const int kr_ = tid >> 3, kc8 = (tid & 7) * 8, kst = KSWZ(kr_, kc8 * 2);
;   const int vr_ = (DV == 128) ? (tid >> 4) : (tid >> 3), vc8 = (DV == 128) ? (tid & 15) * 8 : (tid & 7) * 8;
;   const int vst0 = v_st<NC>(vr_, vc8), vst1 = v_st<NC>((32 + vr_) & 63, vc8);
;   const int vb0 = (int)(uintptr_t)V_lds + v_rd_base(lane);
;   const int kgo = kr_ * LD + kc8, vgo = vr_ * LD + vc8;
;   bf16x8 sk0, sva0, svb0, sk1, sva1, svb1;
;     ...
;   SLOADX(0, 0); asm volatile("s_waitcnt vmcnt(0)" ::: "memory"); SWRITEX(0, 0); SLOADX(1, 64); SLOADX(0, 128); __syncthreads();
;   for (int jj = 0; jj < NT; jj += 2) {
; #pragma unroll
;    for (int par = 0; par < 2; ++par) {
;     const int j = jj + par; const int b = par; const bool act = ACT(j);
;     bf16x8 kf[8];
;     if (act) k_issue(kf, K_lds + b * SHM_K, r32, hi);
;     if (par == 0) { if (j + 1 < NT) { SWRITEX(1, 1); if (j + 3 < NT) SLOADX(1, (j + 3) * 64); } }
.LBB0_271:
	v_mov_b32_e32 v1, v228
	s_lshl_b64 s[50:51], s[36:37], 1
	v_ashrrev_i32_e32 v20, 3, v1
	v_lshlrev_b32_e32 v28, 3, v1
	v_and_b32_e32 v21, 56, v28
	v_ashrrev_i32_e32 v29, 4, v1
	v_mul_lo_u32 v2, v20, s0
	v_or_b32_e32 v2, v2, v21
	v_mul_lo_u32 v3, v29, s0
	s_add_u32 s34, s58, s50
	v_and_or_b32 v4, v28, s33, v3
	v_lshrrev_b32_e32 v5, 3, v1
	v_mul_lo_u32 v2, v5, s0
	v_bfe_u32 v5, v1, 4, 3
	v_and_b32_e32 v6, 7, v1
	v_xor_b32_e32 v5, v5, v6
	v_lshl_or_b32 v2, v5, 3, v2
	v_bfe_u32 v5, v1, 2, 2
	v_bfe_u32 v6, v1, 7, 1
	v_lshl_or_b32 v5, v6, 2, v5
	v_bfe_u32 v6, v1, 4, 1
	v_lshl_or_b32 v5, v6, 3, v5
	v_bfe_u32 v6, v1, 8, 1
	v_lshl_or_b32 v5, v6, 4, v5
	v_mul_lo_u32 v4, v5, s0
	v_bfe_u32 v5, v1, 5, 2
	v_lshl_or_b32 v4, v5, 5, v4
	v_and_b32_e32 v5, 3, v1
	v_lshl_or_b32 v4, v5, 3, v4
	v_ashrrev_i32_e32 v3, 31, v2
	s_addc_u32 s35, s59, s51
	v_lshlrev_b64 v[14:15], 1, v[2:3]
	v_lshl_add_u64 v[16:17], s[34:35], 0, v[14:15]
	v_ashrrev_i32_e32 v5, 31, v4
	s_mov_b32 s35, 0x30000
	v_lshlrev_b64 v[210:211], 1, v[4:5]
	v_add_co_u32_e32 v26, vcc, s35, v16
	v_lshl_add_u64 v[2:3], s[26:27], 0, v[210:211]
	v_lshl_add_u64 v[6:7], s[38:39], 0, v[210:211]
	v_lshl_add_u64 v[18:19], v[208:209], 0, s[50:51]
	v_addc_co_u32_e32 v27, vcc, 0, v17, vcc
	v_readfirstlane_b32 s98, v1
	s_nop 0
	s_lshr_b32 s98, s98, 6
	s_lshl_b32 s98, s98, 10
	s_mov_b32 m0, s98
	s_nop 0
	global_load_lds_dwordx4 v[2:3], off
	s_add_i32 m0, s98, 0x2000
	s_nop 0
	global_load_lds_dwordx4 v[6:7], off
	s_add_i32 m0, s98, 0x8000
	s_nop 0
	global_load_lds_dwordx4 v[16:17], off
	global_load_dwordx4 v[160:163], v[18:19], off
	global_load_dwordx4 v[164:167], v[18:19], off offset:32
	global_load_dwordx4 v[168:171], v[18:19], off offset:64
	global_load_dwordx4 v[172:175], v[18:19], off offset:96
	v_lshlrev_b32_e32 v18, 4, v1
	v_lshlrev_b32_e32 v19, 1, v1
	v_lshlrev_b32_e32 v33, 7, v20
	v_lshlrev_b32_e32 v20, 1, v29
	s_waitcnt vmcnt(0)
	v_add_co_u32_e32 v16, vcc, s24, v16
	v_and_b32_e32 v37, 48, v18
	v_and_b32_e32 v38, 0xc0, v18
	v_and_b32_e32 v39, 32, v19
	v_lshlrev_b32_e32 v40, 1, v21
	v_and_b32_e32 v41, 8, v20
	v_lshl_add_u64 v[18:19], s[40:41], 0, v[210:211]
	v_lshl_add_u64 v[20:21], s[42:43], 0, v[210:211]
	v_lshl_add_u64 v[22:23], s[44:45], 0, v[210:211]
	v_lshl_add_u64 v[24:25], s[46:47], 0, v[210:211]
	v_addc_co_u32_e32 v17, vcc, 0, v17, vcc
	v_readfirstlane_b32 s34, v1
	s_and_b32 s34, s34, 0x3fffffc0
	s_lshl_b32 s34, s34, 2
	s_add_i32 s60, s34, 0
	s_mov_b32 s34, 0xfffff0
	v_and_b32_e32 v32, 0x70, v1
	v_lshrrev_b32_e32 v34, 1, v29
	v_and_b32_e32 v36, 3, v29
	v_and_or_b32 v18, v29, s34, v41
	v_and_or_b32 v19, v29, 48, v41
	v_bfe_u32 v35, v28, 5, 2
	v_and_or_b32 v16, v34, 4, v36
	v_bitop3_b32 v17, v40, v33, v32 bitop3:0xde
	v_lshrrev_b32_e32 v18, 1, v18
	v_lshrrev_b32_e32 v19, 1, v19
	v_lshlrev_b32_e32 v16, 6, v16
	v_add_u32_e32 v217, 0, v17
	v_or_b32_e32 v17, v18, v35
	v_or_b32_e32 v18, v19, v35
	v_and_b32_e32 v30, 31, v1
	v_and_b32_e32 v31, 63, v1
	v_lshrrev_b32_e32 v1, 1, v1
	v_lshlrev_b32_e32 v17, 9, v17
	v_lshl_or_b32 v18, v18, 9, v16
	s_movk_i32 s34, 0x2000
	v_or3_b32 v16, v17, v16, v37
	v_bitop3_b32 v17, v18, s34, v37 bitop3:0x36
	v_and_b32_e32 v220, 16, v1
	s_movk_i32 s34, 0x70
	v_add_u32_e32 v219, 0, v17
	v_and_b32_e32 v1, 0x70, v28
	v_bitop3_b32 v17, v28, v220, s34 bitop3:0x6c
	s_movk_i32 s34, 0x60
	v_add_u32_e32 v218, 0, v16
	v_lshl_add_u32 v16, v30, 7, 0
	v_bitop3_b32 v18, v220, v1, 32 bitop3:0x36
	v_bitop3_b32 v19, v220, v1, 64 bitop3:0x36
	v_bitop3_b32 v20, v220, v1, s34 bitop3:0x36
	v_and_or_b32 v1, v28, s3, v39
	v_lshl_add_u64 v[212:213], s[50:51], 0, v[14:15]
	v_mov_b32_e32 v14, v0
	v_mov_b32_e32 v15, v0
	v_cmp_gt_u32_e64 s[36:37], 32, v31
	v_lshl_add_u32 v221, v30, 2, s60
	v_add3_u32 v222, v38, 0, v1
	v_mov_b32_e32 v1, v0
	v_mov_b32_e32 v2, v0
	v_mov_b32_e32 v3, v0
	v_mov_b32_e32 v4, v0
	v_mov_b32_e32 v5, v0
	v_mov_b32_e32 v6, v0
	v_mov_b32_e32 v7, v0
	v_mov_b32_e32 v8, v0
	v_mov_b32_e32 v9, v0
	v_mov_b32_e32 v10, v0
	v_mov_b32_e32 v11, v0
	v_mov_b32_e32 v12, v0
	v_mov_b32_e32 v13, v0
	v_mov_b32_e32 v224, 0
	v_add_u32_e32 v225, v16, v17
	v_add_u32_e32 v226, v16, v18
	v_add_u32_e32 v227, v16, v19
	v_add_u32_e32 v236, v16, v20
	v_mov_b64_e32 v[78:79], v[14:15]
	v_mov_b64_e32 v[62:63], v[14:15]
	v_mov_b64_e32 v[46:47], v[14:15]
	v_mov_b64_e32 v[30:31], v[14:15]
	v_mov_b64_e32 v[94:95], v[14:15]
	v_add_u32_e32 v223, 0x4000, v222
	s_mov_b32 s62, -2
	s_mov_b64 s[50:51], s[20:21]
	v_mov_b64_e32 v[76:77], v[12:13]
	v_mov_b64_e32 v[74:75], v[10:11]
	v_mov_b64_e32 v[72:73], v[8:9]
	v_mov_b64_e32 v[70:71], v[6:7]
	v_mov_b64_e32 v[68:69], v[4:5]
	v_mov_b64_e32 v[66:67], v[2:3]
	v_mov_b64_e32 v[64:65], v[0:1]
	v_mov_b64_e32 v[60:61], v[12:13]
	v_mov_b64_e32 v[58:59], v[10:11]
	v_mov_b64_e32 v[56:57], v[8:9]
	v_mov_b64_e32 v[54:55], v[6:7]
	v_mov_b64_e32 v[52:53], v[4:5]
	v_mov_b64_e32 v[50:51], v[2:3]
	v_mov_b64_e32 v[48:49], v[0:1]
	v_mov_b64_e32 v[44:45], v[12:13]
	v_mov_b64_e32 v[42:43], v[10:11]
	v_mov_b64_e32 v[40:41], v[8:9]
	v_mov_b64_e32 v[38:39], v[6:7]
	v_mov_b64_e32 v[36:37], v[4:5]
	v_mov_b64_e32 v[34:35], v[2:3]
	v_mov_b64_e32 v[32:33], v[0:1]
	v_mov_b64_e32 v[28:29], v[12:13]
	v_mov_b64_e32 v[26:27], v[10:11]
	v_mov_b64_e32 v[24:25], v[8:9]
	v_mov_b64_e32 v[22:23], v[6:7]
	v_mov_b64_e32 v[20:21], v[4:5]
	v_mov_b64_e32 v[18:19], v[2:3]
	v_mov_b64_e32 v[16:17], v[0:1]
	v_mov_b64_e32 v[92:93], v[12:13]
	v_mov_b64_e32 v[90:91], v[10:11]
	v_mov_b64_e32 v[88:89], v[8:9]
	v_mov_b64_e32 v[86:87], v[6:7]
	v_mov_b64_e32 v[84:85], v[4:5]
	v_mov_b64_e32 v[82:83], v[2:3]
	v_mov_b64_e32 v[80:81], v[0:1]
	v_mov_b32_e32 v112, 0
	v_mov_b32_e32 v113, v224
	v_mov_b32_e32 v114, v224
	v_mov_b32_e32 v115, v224
	v_mov_b32_e32 v116, v224
	v_mov_b32_e32 v117, v224
	v_mov_b32_e32 v118, v224
	v_mov_b32_e32 v119, v224
	v_mov_b32_e32 v120, v224
	v_mov_b32_e32 v121, v224
	v_mov_b32_e32 v122, v224
	v_mov_b32_e32 v123, v224
	v_mov_b32_e32 v124, v224
	v_mov_b32_e32 v125, v224
	v_mov_b32_e32 v126, v224
	v_mov_b32_e32 v127, v224
	s_waitcnt lgkmcnt(0)
	s_barrier
.LBB0_272:
	ds_read_b128 v[128:131], v225 offset:32768
	ds_read_b128 v[108:111], v225 offset:36864
	ds_read_b128 v[104:107], v226 offset:32768
	ds_read_b128 v[100:103], v226 offset:36864
	ds_read_b128 v[96:99], v227 offset:32768
	ds_read_b128 v[10:13], v227 offset:36864
	ds_read_b128 v[2:5], v236 offset:32768
	ds_read_b128 v[6:9], v236 offset:36864
	s_add_i32 s61, s62, 2
	v_lshl_add_u64 v[14:15], s[50:51], 0, v[212:213]
	v_add_co_u32_e32 v14, vcc, 0x1f830400, v14
	v_lshl_add_u64 v[132:133], s[50:51], 0, v[210:211]
	s_add_i32 m0, s98, 0xa000
	v_addc_co_u32_e32 v15, vcc, 0, v15, vcc
	v_add_co_u32_e32 v134, vcc, 0x1f830800, v132
	global_load_lds_dwordx4 v[14:15], off
	s_add_i32 m0, s98, 0x4000
	v_addc_co_u32_e32 v135, vcc, 0, v133, vcc
	v_add_co_u32_e32 v14, vcc, 0x1f848800, v132
	global_load_lds_dwordx4 v[134:135], off
	s_add_i32 m0, s98, 0x6000
	v_addc_co_u32_e32 v15, vcc, 0, v133, vcc
	global_load_lds_dwordx4 v[14:15], off

; #define SBAR() __builtin_amdgcn_sched_barrier(0)
; #define SLOADX(S, k0) do { sk##S = *reinterpret_cast<const bf16x8*>(Kh + (long)(k0) * LD + kgo); sva##S = *reinterpret_cast<const bf16x8*>(Vh + (long)(k0) * LD + vgo); \
;     if constexpr (DV == 128) svb##S = *reinterpret_cast<const bf16x8*>(Vh + (long)((k0) + 32) * LD + vgo); } while (0)
; #define SWRITEX(S, b) do { *(ALAS bf16x8*)(V_lds + (b) * SHM_V + vst0) = sva##S; if constexpr (DV == 128) *(ALAS bf16x8*)(V_lds + (b) * SHM_V + vst1) = svb##S; \
;     *(ALAS bf16x8*)(K_lds + (b) * SHM_K + kst) = sk##S; } while (0)
; #define EXP8(P, BASE) do { _Pragma("unroll") for (int r = 0; r < 8; ++r) P[BASE + r] = __builtin_amdgcn_exp2f(P[BASE + r]); } while (0)
; #define LGKM(n) asm volatile("s_waitcnt lgkmcnt(" #n ")" ::: "memory")
; template <int DV, bool NA>
; __device__ __forceinline__ void attn_core(const bf16_t* __restrict__ Qlane, const bf16_t* __restrict__ Kh, const bf16_t* __restrict__ Vh, const int NT,
;                                           ALAS char* lds, f32x16 (&o)[DV / 32], const NaCtx& na) {
;     ...
;     const int j = jj + par; const int b = par; const bool act = ACT(j);
;     bf16x8 kf[8];
;     if (act) k_issue(kf, K_lds + b * SHM_K, r32, hi);
;     if (par == 0) { if (j + 1 < NT) { SWRITEX(1, 1); if (j + 3 < NT) SLOADX(1, (j + 3) * 64); } }
;     else          { if (j + 1 < NT) { SWRITEX(0, 0); if (j + 3 < NT) SLOADX(0, (j + 3) * 64); } }
;     ...
;       const int vb = vb0 + b * SHM_V;
;       s16x4 LA[8], LB[8]; bf16x8 pa;
;     ...
;       v_issue_k<NC, 0>(LA, vb);
;       EXP8(p0, 0); PK4(p0, 0, pa); SBAR();
;       v_issue_k<NC, 1>(LB, vb); if constexpr (NC == 4) LGKM(8); else LGKM(4); SBAR(); v_mma_k<NC>(o, osum, LA, pa, ones); SBAR();
;       EXP8(p0, 8); PK4(p0, 8, pa); SBAR();
;       v_issue_k<NC, 2>(LA, vb); if constexpr (NC == 4) LGKM(8); else LGKM(4); SBAR(); v_mma_k<NC>(o, osum, LB, pa, ones); SBAR();
;       EXP8(p1, 0); PK4(p1, 0, pa); SBAR();
;       v_issue_k<NC, 3>(LB, vb); if constexpr (NC == 4) LGKM(8); else LGKM(4); SBAR(); v_mma_k<NC>(o, osum, LA, pa, ones); SBAR();
;       EXP8(p1, 8); PK4(p1, 8, pa); SBAR();
;       LGKM(0); SBAR(); v_mma_k<NC>(o, osum, LB, pa, ones);
;     ...
;     }
;     __syncthreads();
.LBB0_276:
	ds_read_b64_tr_b16 v[2:3], v222 offset:0
	ds_read_b64_tr_b16 v[4:5], v222 offset:0x800
	ds_read_b64_tr_b16 v[6:7], v222 offset:0x200
	ds_read_b64_tr_b16 v[8:9], v222 offset:0xa00
	ds_read_b64_tr_b16 v[10:11], v222 offset:0x400
	v_exp_f32_e32 v1, v144
	v_exp_f32_e32 v14, v145
	v_exp_f32_e32 v15, v146
	v_exp_f32_e32 v145, v147
	v_exp_f32_e32 v146, v148
	v_exp_f32_e32 v147, v149
	v_exp_f32_e32 v148, v150
	v_exp_f32_e32 v149, v151
	ds_read_b64_tr_b16 v[12:13], v222 offset:0xc00
	ds_read_b64_tr_b16 v[200:201], v222 offset:0x600
	ds_read_b64_tr_b16 v[202:203], v222 offset:0xe00
	v_cvt_pk_bf16_f32 v144, v1, v14
	v_cvt_pk_bf16_f32 v145, v15, v145
	v_cvt_pk_bf16_f32 v146, v146, v147
	v_cvt_pk_bf16_f32 v147, v148, v149
	s_nop 0
	v_permlane32_swap_b32_e32 v144, v146
	v_permlane32_swap_b32_e32 v145, v147
	s_add_i32 s52, s62, 3
	ds_read_b64_tr_b16 v[148:149], v222 offset:0x1000
	ds_read_b64_tr_b16 v[150:151], v222 offset:0x1800
	ds_read_b64_tr_b16 v[238:239], v222 offset:0x1200
	ds_read_b64_tr_b16 v[240:241], v222 offset:0x1a00
	ds_read_b64_tr_b16 v[242:243], v222 offset:0x1400
	ds_read_b64_tr_b16 v[244:245], v222 offset:0x1c00
	ds_read_b64_tr_b16 v[246:247], v222 offset:0x1600
	ds_read_b64_tr_b16 v[248:249], v222 offset:0x1e00
	s_waitcnt lgkmcnt(8)
	v_mfma_f32_32x32x16_bf16 v[64:79], v[144:147], v[2:5], v[64:79]
	v_mfma_f32_32x32x16_bf16 v[48:63], v[144:147], v[6:9], v[48:63]
	v_mfma_f32_32x32x16_bf16 v[32:47], v[144:147], v[10:13], v[32:47]
	v_mfma_f32_32x32x16_bf16 v[16:31], v[144:147], v[200:203], v[16:31]
	v_exp_f32_e32 v1, v152
	v_exp_f32_e32 v2, v153
	v_exp_f32_e32 v3, v154
	v_exp_f32_e32 v4, v155
	v_exp_f32_e32 v5, v156
	v_exp_f32_e32 v6, v157
	v_exp_f32_e32 v7, v158
	v_exp_f32_e32 v8, v159
	v_cvt_pk_bf16_f32 v2, v1, v2
	v_cvt_pk_bf16_f32 v3, v3, v4
	v_cvt_pk_bf16_f32 v4, v5, v6
	v_cvt_pk_bf16_f32 v5, v7, v8
	s_nop 0
	v_permlane32_swap_b32_e32 v2, v4
	v_permlane32_swap_b32_e32 v3, v5
	ds_read_b64_tr_b16 v[6:7], v222 offset:0x2000
	ds_read_b64_tr_b16 v[8:9], v222 offset:0x2800
	ds_read_b64_tr_b16 v[10:11], v222 offset:0x2200
	ds_read_b64_tr_b16 v[12:13], v222 offset:0x2a00
	ds_read_b64_tr_b16 v[152:153], v222 offset:0x2400
	ds_read_b64_tr_b16 v[154:155], v222 offset:0x2c00
	ds_read_b64_tr_b16 v[156:157], v222 offset:0x2600
	ds_read_b64_tr_b16 v[158:159], v222 offset:0x2e00
	s_waitcnt lgkmcnt(8)
	v_mfma_f32_32x32x16_bf16 v[64:79], v[2:5], v[148:151], v[64:79]
	v_mfma_f32_32x32x16_bf16 v[48:63], v[2:5], v[238:241], v[48:63]
	v_mfma_f32_32x32x16_bf16 v[32:47], v[2:5], v[242:245], v[32:47]
	v_mfma_f32_32x32x16_bf16 v[16:31], v[2:5], v[246:249], v[16:31]
	v_exp_f32_e32 v1, v128
	v_exp_f32_e32 v14, v129
	v_exp_f32_e32 v15, v130
	v_exp_f32_e32 v148, v131
	v_mov_b64_e32 v[130:131], s[10:11]
	v_mov_b64_e32 v[128:129], s[8:9]
	v_exp_f32_e32 v149, v132
	v_exp_f32_e32 v150, v133
	v_mfma_f32_32x32x16_bf16 v[80:95], v[144:147], v[128:131], v[80:95]
	v_exp_f32_e32 v151, v134
	v_exp_f32_e32 v135, v135
	v_cvt_pk_bf16_f32 v132, v1, v14
	v_cvt_pk_bf16_f32 v133, v15, v148
	v_cvt_pk_bf16_f32 v134, v149, v150
	v_cvt_pk_bf16_f32 v135, v151, v135
	s_nop 0
	v_permlane32_swap_b32_e32 v132, v134
	v_permlane32_swap_b32_e32 v133, v135
	ds_read_b64_tr_b16 v[144:145], v222 offset:0x3000
	ds_read_b64_tr_b16 v[146:147], v222 offset:0x3800
	ds_read_b64_tr_b16 v[148:149], v222 offset:0x3200
	ds_read_b64_tr_b16 v[150:151], v222 offset:0x3a00
	ds_read_b64_tr_b16 v[200:201], v222 offset:0x3400
	ds_read_b64_tr_b16 v[202:203], v222 offset:0x3c00
	ds_read_b64_tr_b16 v[238:239], v222 offset:0x3600
	ds_read_b64_tr_b16 v[240:241], v222 offset:0x3e00
	s_waitcnt lgkmcnt(8)
	v_mfma_f32_32x32x16_bf16 v[64:79], v[132:135], v[6:9], v[64:79]
	v_mfma_f32_32x32x16_bf16 v[48:63], v[132:135], v[10:13], v[48:63]
	v_mfma_f32_32x32x16_bf16 v[32:47], v[132:135], v[152:155], v[32:47]
	v_mfma_f32_32x32x16_bf16 v[16:31], v[132:135], v[156:159], v[16:31]
	v_mfma_f32_32x32x16_bf16 v[80:95], v[2:5], v[128:131], v[80:95]
	v_exp_f32_e32 v1, v136
	v_exp_f32_e32 v6, v137
	v_exp_f32_e32 v7, v138
	v_exp_f32_e32 v8, v139
	v_exp_f32_e32 v9, v140
	v_exp_f32_e32 v4, v141
	v_exp_f32_e32 v5, v142
	v_mfma_f32_32x32x16_bf16 v[80:95], v[132:135], v[128:131], v[80:95]
	v_exp_f32_e32 v10, v143
	v_cvt_pk_bf16_f32 v2, v1, v6
	v_cvt_pk_bf16_f32 v3, v7, v8
	v_cvt_pk_bf16_f32 v4, v9, v4
	v_cvt_pk_bf16_f32 v5, v5, v10
	s_nop 0
	v_permlane32_swap_b32_e32 v2, v4
	v_permlane32_swap_b32_e32 v3, v5
	s_waitcnt lgkmcnt(0)
	s_nop 1
	v_mfma_f32_32x32x16_bf16 v[80:95], v[2:5], v[128:131], v[80:95]
	s_waitcnt lgkmcnt(0)
	s_waitcnt vmcnt(0)
	s_barrier
	s_cmpk_gt_u32 s52, 0xfe
	v_mfma_f32_32x32x16_bf16 v[64:79], v[2:5], v[144:147], v[64:79]
	v_mfma_f32_32x32x16_bf16 v[48:63], v[2:5], v[148:151], v[48:63]
	v_mfma_f32_32x32x16_bf16 v[32:47], v[2:5], v[200:203], v[32:47]
	v_mfma_f32_32x32x16_bf16 v[16:31], v[2:5], v[238:241], v[16:31]
	ds_read_b128 v[156:159], v225 offset:40960
	ds_read_b128 v[200:203], v225 offset:45056
	ds_read_b128 v[152:155], v226 offset:40960
	ds_read_b128 v[148:151], v226 offset:45056
	ds_read_b128 v[144:147], v227 offset:40960
	ds_read_b128 v[10:13], v227 offset:45056
	ds_read_b128 v[2:5], v236 offset:40960
	ds_read_b128 v[6:9], v236 offset:45056
	s_cbranch_scc1 .LBB0_279
	v_lshl_add_u64 v[14:15], s[50:51], 0, v[212:213]
	v_add_co_u32_e32 v14, vcc, 0x1f860400, v14
	v_lshl_add_u64 v[128:129], s[50:51], 0, v[210:211]
	s_add_i32 m0, s98, 0x8000
	v_addc_co_u32_e32 v15, vcc, 0, v15, vcc
	v_add_co_u32_e32 v130, vcc, 0x1f860800, v128
	global_load_lds_dwordx4 v[14:15], off
	s_mov_b32 m0, s98
	v_addc_co_u32_e32 v131, vcc, 0, v129, vcc
	v_add_co_u32_e32 v14, vcc, 0x1f878800, v128
	global_load_lds_dwordx4 v[130:131], off
	s_add_i32 m0, s98, 0x2000
	v_addc_co_u32_e32 v15, vcc, 0, v129, vcc
	global_load_lds_dwordx4 v[14:15], off

; #define SBAR() __builtin_amdgcn_sched_barrier(0)
; #define EXP8(P, BASE) do { _Pragma("unroll") for (int r = 0; r < 8; ++r) P[BASE + r] = __builtin_amdgcn_exp2f(P[BASE + r]); } while (0)
; #define LGKM(n) asm volatile("s_waitcnt lgkmcnt(" #n ")" ::: "memory")
; template <int DV, bool NA>
; __device__ __forceinline__ void attn_core(const bf16_t* __restrict__ Qlane, const bf16_t* __restrict__ Kh, const bf16_t* __restrict__ Vh, const int NT,
;                                           ALAS char* lds, f32x16 (&o)[DV / 32], const NaCtx& na) {
;     ...
;       const int vb = vb0 + b * SHM_V;
;       s16x4 LA[8], LB[8]; bf16x8 pa;
;     ...
;       v_issue_k<NC, 0>(LA, vb);
;       EXP8(p0, 0); PK4(p0, 0, pa); SBAR();
;       v_issue_k<NC, 1>(LB, vb); if constexpr (NC == 4) LGKM(8); else LGKM(4); SBAR(); v_mma_k<NC>(o, osum, LA, pa, ones); SBAR();
;       EXP8(p0, 8); PK4(p0, 8, pa); SBAR();
;       v_issue_k<NC, 2>(LA, vb); if constexpr (NC == 4) LGKM(8); else LGKM(4); SBAR(); v_mma_k<NC>(o, osum, LB, pa, ones); SBAR();
;       EXP8(p1, 0); PK4(p1, 0, pa); SBAR();
;       v_issue_k<NC, 3>(LB, vb); if constexpr (NC == 4) LGKM(8); else LGKM(4); SBAR(); v_mma_k<NC>(o, osum, LA, pa, ones); SBAR();
;       EXP8(p1, 8); PK4(p1, 8, pa); SBAR();
;       LGKM(0); SBAR(); v_mma_k<NC>(o, osum, LB, pa, ones);
;     ...
;     }
;     __syncthreads();
.LBB0_280:
	ds_read_b64_tr_b16 v[2:3], v223 offset:0
	ds_read_b64_tr_b16 v[4:5], v223 offset:0x800
	ds_read_b64_tr_b16 v[6:7], v223 offset:0x200
	ds_read_b64_tr_b16 v[8:9], v223 offset:0xa00
	ds_read_b64_tr_b16 v[10:11], v223 offset:0x400
	ds_read_b64_tr_b16 v[12:13], v223 offset:0xc00
	v_exp_f32_e32 v1, v128
	v_exp_f32_e32 v14, v129
	v_exp_f32_e32 v15, v130
	v_exp_f32_e32 v129, v131
	v_exp_f32_e32 v130, v132
	v_exp_f32_e32 v131, v133
	v_exp_f32_e32 v132, v134
	v_exp_f32_e32 v133, v135
	ds_read_b64_tr_b16 v[144:145], v223 offset:0x600
	ds_read_b64_tr_b16 v[146:147], v223 offset:0xe00
	v_cvt_pk_bf16_f32 v128, v1, v14
	v_cvt_pk_bf16_f32 v129, v15, v129
	v_cvt_pk_bf16_f32 v130, v130, v131
	v_cvt_pk_bf16_f32 v131, v132, v133
	s_nop 0
	v_permlane32_swap_b32_e32 v128, v130
	v_permlane32_swap_b32_e32 v129, v131
	ds_read_b64_tr_b16 v[132:133], v223 offset:0x1000
	ds_read_b64_tr_b16 v[134:135], v223 offset:0x1800
	ds_read_b64_tr_b16 v[148:149], v223 offset:0x1200
	ds_read_b64_tr_b16 v[150:151], v223 offset:0x1a00
	ds_read_b64_tr_b16 v[152:153], v223 offset:0x1400
	ds_read_b64_tr_b16 v[154:155], v223 offset:0x1c00
	ds_read_b64_tr_b16 v[156:157], v223 offset:0x1600
	ds_read_b64_tr_b16 v[158:159], v223 offset:0x1e00
	s_waitcnt lgkmcnt(8)
	v_mfma_f32_32x32x16_bf16 v[64:79], v[128:131], v[2:5], v[64:79]
	v_mfma_f32_32x32x16_bf16 v[48:63], v[128:131], v[6:9], v[48:63]
	v_mfma_f32_32x32x16_bf16 v[32:47], v[128:131], v[10:13], v[32:47]
	v_mfma_f32_32x32x16_bf16 v[16:31], v[128:131], v[144:147], v[16:31]
	v_exp_f32_e32 v1, v136
	v_exp_f32_e32 v2, v137
	v_exp_f32_e32 v3, v138
	v_exp_f32_e32 v4, v139
	v_exp_f32_e32 v5, v140
	v_exp_f32_e32 v6, v141
	v_exp_f32_e32 v7, v142
	v_exp_f32_e32 v8, v143
	v_cvt_pk_bf16_f32 v2, v1, v2
	v_cvt_pk_bf16_f32 v3, v3, v4
	v_cvt_pk_bf16_f32 v4, v5, v6
	v_cvt_pk_bf16_f32 v5, v7, v8
	s_nop 0
	v_permlane32_swap_b32_e32 v2, v4
	v_permlane32_swap_b32_e32 v3, v5
	ds_read_b64_tr_b16 v[6:7], v223 offset:0x2000
	ds_read_b64_tr_b16 v[8:9], v223 offset:0x2800
	ds_read_b64_tr_b16 v[10:11], v223 offset:0x2200
	ds_read_b64_tr_b16 v[12:13], v223 offset:0x2a00
	ds_read_b64_tr_b16 v[136:137], v223 offset:0x2400
	ds_read_b64_tr_b16 v[138:139], v223 offset:0x2c00
	ds_read_b64_tr_b16 v[140:141], v223 offset:0x2600
	ds_read_b64_tr_b16 v[142:143], v223 offset:0x2e00
	s_waitcnt lgkmcnt(8)
	v_mfma_f32_32x32x16_bf16 v[64:79], v[2:5], v[132:135], v[64:79]
	v_mfma_f32_32x32x16_bf16 v[48:63], v[2:5], v[148:151], v[48:63]
	v_mfma_f32_32x32x16_bf16 v[32:47], v[2:5], v[152:155], v[32:47]
	v_mfma_f32_32x32x16_bf16 v[16:31], v[2:5], v[156:159], v[16:31]
	v_exp_f32_e32 v1, v96
	v_exp_f32_e32 v14, v97
	v_exp_f32_e32 v15, v98
	v_exp_f32_e32 v132, v99
	v_mov_b64_e32 v[98:99], s[10:11]
	v_mov_b64_e32 v[96:97], s[8:9]
	v_exp_f32_e32 v133, v100
	v_exp_f32_e32 v134, v101
	v_mfma_f32_32x32x16_bf16 v[80:95], v[128:131], v[96:99], v[80:95]
	v_exp_f32_e32 v135, v102
	v_exp_f32_e32 v103, v103
	v_cvt_pk_bf16_f32 v100, v1, v14
	v_cvt_pk_bf16_f32 v101, v15, v132
	v_cvt_pk_bf16_f32 v102, v133, v134
	v_cvt_pk_bf16_f32 v103, v135, v103
	s_nop 0
	v_permlane32_swap_b32_e32 v100, v102
	v_permlane32_swap_b32_e32 v101, v103
	ds_read_b64_tr_b16 v[128:129], v223 offset:0x3000
	ds_read_b64_tr_b16 v[130:131], v223 offset:0x3800
	ds_read_b64_tr_b16 v[132:133], v223 offset:0x3200
	ds_read_b64_tr_b16 v[134:135], v223 offset:0x3a00
	ds_read_b64_tr_b16 v[144:145], v223 offset:0x3400
	ds_read_b64_tr_b16 v[146:147], v223 offset:0x3c00
	ds_read_b64_tr_b16 v[148:149], v223 offset:0x3600
	ds_read_b64_tr_b16 v[150:151], v223 offset:0x3e00
	s_waitcnt lgkmcnt(8)
	v_mfma_f32_32x32x16_bf16 v[64:79], v[100:103], v[6:9], v[64:79]
	v_mfma_f32_32x32x16_bf16 v[48:63], v[100:103], v[10:13], v[48:63]
	v_mfma_f32_32x32x16_bf16 v[32:47], v[100:103], v[136:139], v[32:47]
	v_mfma_f32_32x32x16_bf16 v[16:31], v[100:103], v[140:143], v[16:31]
	v_mfma_f32_32x32x16_bf16 v[80:95], v[2:5], v[96:99], v[80:95]
	v_exp_f32_e32 v1, v104
	v_exp_f32_e32 v6, v105
	v_exp_f32_e32 v7, v106
	v_exp_f32_e32 v8, v107
	v_exp_f32_e32 v9, v108
	v_exp_f32_e32 v4, v109
	v_exp_f32_e32 v5, v110
	v_mfma_f32_32x32x16_bf16 v[80:95], v[100:103], v[96:99], v[80:95]
	v_exp_f32_e32 v10, v111
	v_cvt_pk_bf16_f32 v2, v1, v6
	v_cvt_pk_bf16_f32 v3, v7, v8
	v_cvt_pk_bf16_f32 v4, v9, v4
	v_cvt_pk_bf16_f32 v5, v5, v10
	s_nop 0
	v_permlane32_swap_b32_e32 v2, v4
	v_permlane32_swap_b32_e32 v3, v5
	s_waitcnt lgkmcnt(0)
	s_nop 1
	v_mfma_f32_32x32x16_bf16 v[80:95], v[2:5], v[96:99], v[80:95]
	s_add_u32 s50, s50, 0x60000
	s_addc_u32 s51, s51, 0
	s_cmpk_lt_u32 s61, 0xfe
	s_waitcnt vmcnt(0)
	s_barrier
	v_mfma_f32_32x32x16_bf16 v[64:79], v[2:5], v[128:131], v[64:79]
	v_mfma_f32_32x32x16_bf16 v[48:63], v[2:5], v[132:135], v[48:63]
	v_mfma_f32_32x32x16_bf16 v[32:47], v[2:5], v[144:147], v[32:47]
	v_mfma_f32_32x32x16_bf16 v[16:31], v[2:5], v[148:151], v[16:31]
	s_cbranch_scc0 .LBB0_288
	s_mov_b32 s62, s61
	s_branch .LBB0_272
